# barrier 1 wait also warms L2 with the workgroup's first 32 x rows and the w_in gate-column lines (inputs that do not depend on P0)
# speedup vs baseline: 1.0008x; 1.0008x over previous
; DI int fresh_tid() { int t = threadIdx.x; asm volatile("" : "+v"(t)); return t; }
; DI void phase1(const Params& p, unsigned char* smem) {
;     ...
;     for (int i = 0; i < 4; ++i)
; #pragma unroll
;         for (int e = 0; e < 4; ++e) {
;             const float* wp = p.in[4] + (size_t)(i * 256 + lane * 4 + e) * 4616 + 2048;
;             gw0[i * 4 + e] = *(const float4*)wp; gw1[i * 4 + e] = *(const float4*)(wp + 4);
;         }
;     float* ig = (float*)(ws + OFF_IG);
;     float* lf = (float*)(ws + OFF_LOGF);
;     for (int row0 = (blockIdx.x * 8 + wid) * 4; row0 < T_; row0 += gridDim.x * 32) {
;         float vv[4][16];
; #pragma unroll
;         for (int rr = 0; rr < 4; ++rr)
; #pragma unroll
;             for (int i = 0; i < 4; ++i) { float4 t = *(const float4*)(p.in[0] + (size_t)(row0 + rr) * 1024 + i * 256 + lane * 4); vv[rr][4 * i] = t.x; vv[rr][4 * i + 1] = t.y; vv[rr][4 * i + 2] = t.z; vv[rr][4 * i + 3] = t.w; }
; DI void xcd_barrier(unsigned* bar, volatile __attribute__((address_space(3))) unsigned* st) {
;     asm volatile("s_waitcnt vmcnt(0)" ::: "memory");
;     __syncthreads();
;     if (fresh_tid() == 0) {
.LBB0_132:
	s_or_b64 exec, exec, s[6:7]
	s_waitcnt vmcnt(0)
	v_mov_b32_e32 v0, v250
	s_barrier
	s_getpc_b64 vcc
	v_mov_b32_e32 v2, vcc_lo
	v_mov_b32_e32 v3, vcc_hi
	v_cmp_lt_u32_e32 vcc, 63, v0
	s_and_saveexec_b64 s[0:1], vcc
	s_cbranch_execz .Lcpf_s1
	v_lshlrev_b32_e32 v1, 6, v0
	v_subrev_u32_e32 v1, 0x1000, v1
	v_add_co_u32_e32 v2, vcc, v2, v1
	s_nop 1
	v_addc_co_u32_e32 v3, vcc, 0, v3, vcc
	global_load_dword v4, v[2:3], off
	v_add_co_u32_e32 v2, vcc, 0x7000, v2
	s_nop 1
	v_addc_co_u32_e32 v3, vcc, 0, v3, vcc
	global_load_dword v5, v[2:3], off
	v_readlane_b32 s4, v254, 4
	v_readlane_b32 s5, v254, 5
	v_readlane_b32 s6, v254, 12
	v_readlane_b32 s7, v254, 13
	s_lshl_b32 s8, s2, 17
	v_lshlrev_b32_e32 v1, 6, v0
	s_add_u32 s4, s4, s8
	s_addc_u32 s5, s5, 0
	v_subrev_u32_e32 v1, 0x1000, v1
	s_add_u32 s6, s6, 0x2000
	s_addc_u32 s7, s7, 0
	global_load_dword v4, v1, s[4:5]
	s_add_u32 s4, s4, 0x7000
	s_addc_u32 s5, s5, 0
	v_subrev_u32_e32 v2, 64, v0
	global_load_dword v4, v1, s[4:5]
	s_add_u32 s4, s4, 0x7000
	s_addc_u32 s5, s5, 0
	v_mul_u32_u24_e32 v3, 0x4820, v2
	global_load_dword v4, v1, s[4:5]
	s_add_u32 s4, s4, 0x7000
	s_addc_u32 s5, s5, 0
	global_load_dword v5, v3, s[6:7]
	global_load_dword v4, v1, s[4:5]
	s_add_u32 s4, s4, 0x7000
	s_addc_u32 s5, s5, 0
	v_add_u32_e32 v3, 0x1c0, v2
	v_min_u32_e32 v3, 0x3ff, v3
	v_mul_u32_u24_e32 v3, 0x4820, v3
	global_load_dword v4, v1, s[4:5]
	global_load_dword v5, v3, s[6:7]
	v_add_u32_e32 v3, 0x380, v2
	v_min_u32_e32 v3, 0x3ff, v3
	v_mul_u32_u24_e32 v3, 0x4820, v3
	global_load_dword v5, v3, s[6:7]
